# mem items remapped so the 16 WGs sharing one (batch,head) K/V tile share an XCD L2
# baseline (speedup 1.0000x reference)
.LBB0_159:
	s_and_b32 s98, s25, 7
	s_lshl_b32 s98, s98, 1
	s_lshr_b32 s99, s25, 7
	s_add_i32 s98, s98, s99
	s_lshl_b32 s98, s98, 4
	s_bfe_u32 s99, s25, 0x40003
	s_or_b32 s98, s98, s99
	s_ashr_i32 s4, s98, 6
	s_add_i32 s0, s4, s13
	s_ashr_i32 s1, s0, 31
	s_lshl_b64 s[0:1], s[0:1], 19
	s_add_u32 s5, s15, s0
	s_addc_u32 s7, s20, s1
	s_and_b32 s98, s25, 7
	s_lshl_b32 s98, s98, 1
	s_lshr_b32 s99, s25, 7
	s_add_i32 s98, s98, s99
	s_lshl_b32 s98, s98, 4
	s_bfe_u32 s99, s25, 0x40003
	s_or_b32 s98, s98, s99
	s_lshl_b32 s6, s98, 4
	s_and_b32 s28, s6, 0x300
	s_lshl_b32 s6, s28, 1
	s_add_u32 s6, s5, s6
	s_addc_u32 s7, s7, 0
	v_mov_b32_e32 v131, v1
	v_lshl_add_u64 v[18:19], s[6:7], 0, v[130:131]
	s_mov_b32 s5, 0
	s_mov_b64 s[6:7], -1
.LBB0_160:
	v_cndmask_b32_e64 v2, 0, 1, s[6:7]
	v_cmp_ne_u32_e32 vcc, 1, v2
	v_add_u32_e32 v2, s5, v208
	v_ashrrev_i32_e32 v20, 5, v2
	v_add_u32_e32 v6, s5, v127
	v_ashrrev_i32_e32 v21, 31, v20
	v_ashrrev_i32_e32 v22, 5, v6
	v_add_u32_e32 v10, s5, v136
	v_lshlrev_b64 v[2:3], 11, v[20:21]
	v_ashrrev_i32_e32 v23, 31, v22
	v_ashrrev_i32_e32 v24, 5, v10
	v_add_u32_e32 v14, s5, v137
	v_lshl_add_u64 v[2:3], v[18:19], 0, v[2:3]
	v_lshlrev_b64 v[6:7], 11, v[22:23]
	v_ashrrev_i32_e32 v25, 31, v24
	v_ashrrev_i32_e32 v26, 5, v14
	v_add_u32_e32 v21, s5, v141
	flat_load_dwordx4 v[2:5], v[2:3]
	v_lshl_add_u64 v[6:7], v[18:19], 0, v[6:7]
	v_lshlrev_b64 v[10:11], 11, v[24:25]
	v_ashrrev_i32_e32 v27, 31, v26
	v_ashrrev_i32_e32 v44, 5, v21
	v_add_u32_e32 v21, s5, v142
	flat_load_dwordx4 v[6:9], v[6:7]
	v_lshl_add_u64 v[10:11], v[18:19], 0, v[10:11]
	v_lshlrev_b64 v[14:15], 11, v[26:27]
	v_ashrrev_i32_e32 v45, 31, v44
	v_ashrrev_i32_e32 v46, 5, v21
	v_add_u32_e32 v21, s5, v143
	flat_load_dwordx4 v[10:13], v[10:11]
	v_lshl_add_u64 v[14:15], v[18:19], 0, v[14:15]
	v_lshlrev_b64 v[28:29], 11, v[44:45]
	v_ashrrev_i32_e32 v47, 31, v46
	v_ashrrev_i32_e32 v48, 5, v21
	flat_load_dwordx4 v[14:17], v[14:15]
	v_lshl_add_u64 v[28:29], v[18:19], 0, v[28:29]
	v_lshlrev_b64 v[32:33], 11, v[46:47]
	v_ashrrev_i32_e32 v49, 31, v48
	v_add_u32_e32 v21, s5, v144
	flat_load_dwordx4 v[28:31], v[28:29]
	v_lshl_add_u64 v[32:33], v[18:19], 0, v[32:33]
	v_lshlrev_b64 v[36:37], 11, v[48:49]
	v_ashrrev_i32_e32 v50, 5, v21
	flat_load_dwordx4 v[32:35], v[32:33]
	v_lshl_add_u64 v[36:37], v[18:19], 0, v[36:37]
	v_ashrrev_i32_e32 v51, 31, v50
	flat_load_dwordx4 v[36:39], v[36:37]
	v_lshlrev_b64 v[40:41], 11, v[50:51]
	v_lshl_add_u64 v[40:41], v[18:19], 0, v[40:41]
	flat_load_dwordx4 v[40:43], v[40:41]
	v_mad_u64_u32 v[20:21], s[6:7], v20, s85, v[126:127]
	s_movk_i32 s5, 0x1000
	s_and_b64 vcc, exec, vcc
	s_waitcnt vmcnt(0) lgkmcnt(0)
	ds_write_b128 v20, v[2:5]
	v_mad_u64_u32 v[2:3], s[6:7], v22, s85, v[126:127]
	ds_write_b128 v2, v[6:9]
	v_mad_u64_u32 v[2:3], s[6:7], v24, s85, v[126:127]
	ds_write_b128 v2, v[10:13]
	v_mad_u64_u32 v[2:3], s[6:7], v26, s85, v[126:127]
	ds_write_b128 v2, v[14:17]
	v_mad_u64_u32 v[2:3], s[6:7], v44, s85, v[126:127]
	ds_write_b128 v2, v[28:31]
	v_mad_u64_u32 v[2:3], s[6:7], v46, s85, v[126:127]
	ds_write_b128 v2, v[32:35]
	v_mad_u64_u32 v[2:3], s[6:7], v48, s85, v[126:127]
	ds_write_b128 v2, v[36:39]
	v_mad_u64_u32 v[2:3], s[6:7], v50, s85, v[126:127]
	s_mov_b64 s[6:7], 0
	ds_write_b128 v2, v[40:43]
	s_cbranch_vccz .LBB0_160
	s_and_b32 s98, s25, 7
	s_lshl_b32 s98, s98, 1
	s_lshr_b32 s99, s25, 7
	s_add_i32 s98, s98, s99
	s_lshl_b32 s98, s98, 4
	s_bfe_u32 s99, s25, 0x40003
	s_or_b32 s98, s98, s99
	s_lshl_b32 s5, s98, 8
	s_and_b32 s6, s5, 0xf00
	s_ashr_i32 s5, s4, 31
	s_lshl_b64 s[4:5], s[4:5], 12
	s_or_b32 s4, s4, s6
	v_lshl_add_u64 v[2:3], s[4:5], 0, v[128:129]
	v_mov_b64_e32 v[4:5], s[26:27]
	v_mad_u64_u32 v[4:5], s[4:5], v2, s83, v[4:5]
	v_mad_i32_i24 v5, v3, s83, v5
	s_lshl_b32 s36, s28, 1
	v_lshl_add_u64 v[2:3], v[4:5], 0, s[36:37]
	s_mov_b64 s[4:5], 0x2200
	v_lshl_add_u64 v[134:135], v[2:3], 0, s[4:5]
	v_lshl_add_u64 v[132:133], v[134:135], 0, v[0:1]
	s_waitcnt lgkmcnt(0)
	s_barrier
	s_mov_b32 s5, 0x210000
	s_lshl_b32 s4, s28, 9
	s_add_u32 s0, s21, s0
	s_addc_u32 s1, s24, s1
	s_add_u32 s0, s0, s4
	s_addc_u32 s1, s1, 0
	global_load_dwordx4 v[98:101], v[132:133], off
	global_load_dwordx4 v[102:105], v[132:133], off offset:64
	global_load_dwordx4 v[106:109], v[132:133], off offset:128
	global_load_dwordx4 v[110:113], v[132:133], off offset:192
	global_load_dwordx4 v[114:117], v[132:133], off offset:256
	global_load_dwordx4 v[118:121], v[132:133], off offset:320
	global_load_dwordx4 v[122:125], v[132:133], off offset:384
	global_load_dwordx4 v[224:227], v[132:133], off offset:448
	v_and_b32_e32 v244, 15, v195
	v_lshrrev_b32_e32 v245, 4, v195
	v_and_b32_e32 v245, 3, v245
	v_mul_u32_u24_e32 v244, 0x210, v244
	v_lshl_add_u32 v244, v245, 4, v244
	v_add_u32_e32 v245, 0x10800, v244
	v_add_co_u32_e32 v246, vcc, s5, v132
	s_nop 1
	v_addc_co_u32_e32 v247, vcc, 0, v133, vcc
	s_waitcnt vmcnt(0)
	ds_read_b128 v[2:5], v244
	ds_read_b128 v[6:9], v244 offset:64
	ds_read_b128 v[10:13], v244 offset:128
	ds_read_b128 v[14:17], v244 offset:192
	ds_read_b128 v[18:21], v244 offset:256
	ds_read_b128 v[22:25], v244 offset:320
	ds_read_b128 v[26:29], v244 offset:384
	ds_read_b128 v[30:33], v244 offset:448
	s_waitcnt lgkmcnt(7)
	v_mfma_f32_16x16x32_bf16 v[34:37], v[2:5], v[98:101], 0
	ds_read_b128 v[2:5], v244 offset:8448
	s_waitcnt lgkmcnt(7)
	v_mfma_f32_16x16x32_bf16 v[34:37], v[6:9], v[102:105], v[34:37]
	ds_read_b128 v[6:9], v244 offset:8512
	s_waitcnt lgkmcnt(7)
	v_mfma_f32_16x16x32_bf16 v[34:37], v[10:13], v[106:109], v[34:37]
	ds_read_b128 v[10:13], v244 offset:8576
	s_waitcnt lgkmcnt(7)
	v_mfma_f32_16x16x32_bf16 v[34:37], v[14:17], v[110:113], v[34:37]
	ds_read_b128 v[14:17], v244 offset:8640
	s_waitcnt lgkmcnt(7)
	v_mfma_f32_16x16x32_bf16 v[34:37], v[18:21], v[114:117], v[34:37]
	ds_read_b128 v[18:21], v244 offset:8704
	s_waitcnt lgkmcnt(7)
	v_mfma_f32_16x16x32_bf16 v[34:37], v[22:25], v[118:121], v[34:37]
	ds_read_b128 v[22:25], v244 offset:8768
	s_waitcnt lgkmcnt(7)
	v_mfma_f32_16x16x32_bf16 v[34:37], v[26:29], v[122:125], v[34:37]
	ds_read_b128 v[26:29], v244 offset:8832
	s_waitcnt lgkmcnt(7)
	v_mfma_f32_16x16x32_bf16 v[34:37], v[30:33], v[224:227], v[34:37]
	ds_read_b128 v[30:33], v244 offset:8896
	s_waitcnt lgkmcnt(7)
	v_mfma_f32_16x16x32_bf16 v[38:41], v[2:5], v[98:101], 0
	ds_read_b128 v[2:5], v244 offset:16896
	s_waitcnt lgkmcnt(7)
	v_mfma_f32_16x16x32_bf16 v[38:41], v[6:9], v[102:105], v[38:41]
	ds_read_b128 v[6:9], v244 offset:16960
	s_waitcnt lgkmcnt(7)
	v_mfma_f32_16x16x32_bf16 v[38:41], v[10:13], v[106:109], v[38:41]
	ds_read_b128 v[10:13], v244 offset:17024
	s_waitcnt lgkmcnt(7)
	v_mfma_f32_16x16x32_bf16 v[38:41], v[14:17], v[110:113], v[38:41]
	ds_read_b128 v[14:17], v244 offset:17088
	s_waitcnt lgkmcnt(7)
	v_mfma_f32_16x16x32_bf16 v[38:41], v[18:21], v[114:117], v[38:41]
	ds_read_b128 v[18:21], v244 offset:17152
	s_waitcnt lgkmcnt(7)
	v_mfma_f32_16x16x32_bf16 v[38:41], v[22:25], v[118:121], v[38:41]
	ds_read_b128 v[22:25], v244 offset:17216
	s_waitcnt lgkmcnt(7)
	v_mfma_f32_16x16x32_bf16 v[38:41], v[26:29], v[122:125], v[38:41]
	ds_read_b128 v[26:29], v244 offset:17280
	s_waitcnt lgkmcnt(7)
	v_mfma_f32_16x16x32_bf16 v[38:41], v[30:33], v[224:227], v[38:41]
	ds_read_b128 v[30:33], v244 offset:17344
	s_waitcnt lgkmcnt(7)
	v_mfma_f32_16x16x32_bf16 v[42:45], v[2:5], v[98:101], 0
	ds_read_b128 v[2:5], v244 offset:25344
	s_waitcnt lgkmcnt(7)
	v_mfma_f32_16x16x32_bf16 v[42:45], v[6:9], v[102:105], v[42:45]
	ds_read_b128 v[6:9], v244 offset:25408
	s_waitcnt lgkmcnt(7)
	v_mfma_f32_16x16x32_bf16 v[42:45], v[10:13], v[106:109], v[42:45]
	ds_read_b128 v[10:13], v244 offset:25472
	s_waitcnt lgkmcnt(7)
	v_mfma_f32_16x16x32_bf16 v[42:45], v[14:17], v[110:113], v[42:45]
	ds_read_b128 v[14:17], v244 offset:25536
	s_waitcnt lgkmcnt(7)
	v_mfma_f32_16x16x32_bf16 v[42:45], v[18:21], v[114:117], v[42:45]
	ds_read_b128 v[18:21], v244 offset:25600
	s_waitcnt lgkmcnt(7)
	v_mfma_f32_16x16x32_bf16 v[42:45], v[22:25], v[118:121], v[42:45]
	ds_read_b128 v[22:25], v244 offset:25664
	s_waitcnt lgkmcnt(7)
	v_mfma_f32_16x16x32_bf16 v[42:45], v[26:29], v[122:125], v[42:45]
	ds_read_b128 v[26:29], v244 offset:25728
	s_waitcnt lgkmcnt(7)
	v_mfma_f32_16x16x32_bf16 v[42:45], v[30:33], v[224:227], v[42:45]
	ds_read_b128 v[30:33], v244 offset:25792
	s_waitcnt lgkmcnt(7)
	v_mfma_f32_16x16x32_bf16 v[46:49], v[2:5], v[98:101], 0
	ds_read_b128 v[2:5], v244 offset:33792
	s_waitcnt lgkmcnt(7)
	v_mfma_f32_16x16x32_bf16 v[46:49], v[6:9], v[102:105], v[46:49]
	ds_read_b128 v[6:9], v244 offset:33856
	s_waitcnt lgkmcnt(7)
	v_mfma_f32_16x16x32_bf16 v[46:49], v[10:13], v[106:109], v[46:49]
	ds_read_b128 v[10:13], v244 offset:33920
	s_waitcnt lgkmcnt(7)
	v_mfma_f32_16x16x32_bf16 v[46:49], v[14:17], v[110:113], v[46:49]
	ds_read_b128 v[14:17], v244 offset:33984
	s_waitcnt lgkmcnt(7)
	v_mfma_f32_16x16x32_bf16 v[46:49], v[18:21], v[114:117], v[46:49]
	ds_read_b128 v[18:21], v244 offset:34048
	s_waitcnt lgkmcnt(7)
	v_mfma_f32_16x16x32_bf16 v[46:49], v[22:25], v[118:121], v[46:49]
	ds_read_b128 v[22:25], v244 offset:34112
	s_waitcnt lgkmcnt(7)
	v_mfma_f32_16x16x32_bf16 v[46:49], v[26:29], v[122:125], v[46:49]
	ds_read_b128 v[26:29], v244 offset:34176
	s_waitcnt lgkmcnt(7)
	v_mfma_f32_16x16x32_bf16 v[46:49], v[30:33], v[224:227], v[46:49]
	ds_read_b128 v[30:33], v244 offset:34240
	s_waitcnt lgkmcnt(7)
	v_mfma_f32_16x16x32_bf16 v[50:53], v[2:5], v[98:101], 0
	ds_read_b128 v[2:5], v244 offset:42240
	s_waitcnt lgkmcnt(7)
	v_mfma_f32_16x16x32_bf16 v[50:53], v[6:9], v[102:105], v[50:53]
	ds_read_b128 v[6:9], v244 offset:42304
	s_waitcnt lgkmcnt(7)
	v_mfma_f32_16x16x32_bf16 v[50:53], v[10:13], v[106:109], v[50:53]
	ds_read_b128 v[10:13], v244 offset:42368
	s_waitcnt lgkmcnt(7)
	v_mfma_f32_16x16x32_bf16 v[50:53], v[14:17], v[110:113], v[50:53]
	ds_read_b128 v[14:17], v244 offset:42432
	s_waitcnt lgkmcnt(7)
	v_mfma_f32_16x16x32_bf16 v[50:53], v[18:21], v[114:117], v[50:53]
	ds_read_b128 v[18:21], v244 offset:42496
	s_waitcnt lgkmcnt(7)
	v_mfma_f32_16x16x32_bf16 v[50:53], v[22:25], v[118:121], v[50:53]
	ds_read_b128 v[22:25], v244 offset:42560
	s_waitcnt lgkmcnt(7)
	v_mfma_f32_16x16x32_bf16 v[50:53], v[26:29], v[122:125], v[50:53]
	ds_read_b128 v[26:29], v244 offset:42624
	s_waitcnt lgkmcnt(7)
	v_mfma_f32_16x16x32_bf16 v[50:53], v[30:33], v[224:227], v[50:53]
	ds_read_b128 v[30:33], v244 offset:42688
	s_waitcnt lgkmcnt(7)
	v_mfma_f32_16x16x32_bf16 v[54:57], v[2:5], v[98:101], 0
	ds_read_b128 v[2:5], v244 offset:50688
	s_waitcnt lgkmcnt(7)
	v_mfma_f32_16x16x32_bf16 v[54:57], v[6:9], v[102:105], v[54:57]
	ds_read_b128 v[6:9], v244 offset:50752
	s_waitcnt lgkmcnt(7)
	v_mfma_f32_16x16x32_bf16 v[54:57], v[10:13], v[106:109], v[54:57]
	ds_read_b128 v[10:13], v244 offset:50816
	s_waitcnt lgkmcnt(7)
	v_mfma_f32_16x16x32_bf16 v[54:57], v[14:17], v[110:113], v[54:57]
	ds_read_b128 v[14:17], v244 offset:50880
	s_waitcnt lgkmcnt(7)
	v_mfma_f32_16x16x32_bf16 v[54:57], v[18:21], v[114:117], v[54:57]
	ds_read_b128 v[18:21], v244 offset:50944
	s_waitcnt lgkmcnt(7)
	v_mfma_f32_16x16x32_bf16 v[54:57], v[22:25], v[118:121], v[54:57]
	ds_read_b128 v[22:25], v244 offset:51008
	s_waitcnt lgkmcnt(7)
	v_mfma_f32_16x16x32_bf16 v[54:57], v[26:29], v[122:125], v[54:57]
	ds_read_b128 v[26:29], v244 offset:51072
	s_waitcnt lgkmcnt(7)
	v_mfma_f32_16x16x32_bf16 v[54:57], v[30:33], v[224:227], v[54:57]
	ds_read_b128 v[30:33], v244 offset:51136
	s_waitcnt lgkmcnt(7)
	v_mfma_f32_16x16x32_bf16 v[58:61], v[2:5], v[98:101], 0
	ds_read_b128 v[2:5], v244 offset:59136
	s_waitcnt lgkmcnt(7)
	v_mfma_f32_16x16x32_bf16 v[58:61], v[6:9], v[102:105], v[58:61]
	ds_read_b128 v[6:9], v244 offset:59200
	s_waitcnt lgkmcnt(7)
	v_mfma_f32_16x16x32_bf16 v[58:61], v[10:13], v[106:109], v[58:61]
	ds_read_b128 v[10:13], v244 offset:59264
	s_waitcnt lgkmcnt(7)
	v_mfma_f32_16x16x32_bf16 v[58:61], v[14:17], v[110:113], v[58:61]
	ds_read_b128 v[14:17], v244 offset:59328
	s_waitcnt lgkmcnt(7)
	v_mfma_f32_16x16x32_bf16 v[58:61], v[18:21], v[114:117], v[58:61]
	ds_read_b128 v[18:21], v244 offset:59392
	s_waitcnt lgkmcnt(7)
	v_mfma_f32_16x16x32_bf16 v[58:61], v[22:25], v[118:121], v[58:61]
	ds_read_b128 v[22:25], v244 offset:59456
	s_waitcnt lgkmcnt(7)
	v_mfma_f32_16x16x32_bf16 v[58:61], v[26:29], v[122:125], v[58:61]
	ds_read_b128 v[26:29], v244 offset:59520
	s_waitcnt lgkmcnt(7)
	v_mfma_f32_16x16x32_bf16 v[58:61], v[30:33], v[224:227], v[58:61]
	ds_read_b128 v[30:33], v244 offset:59584
	s_waitcnt lgkmcnt(7)
	v_mfma_f32_16x16x32_bf16 v[62:65], v[2:5], v[98:101], 0
	ds_read_b128 v[2:5], v245
	s_waitcnt lgkmcnt(7)
	v_mfma_f32_16x16x32_bf16 v[62:65], v[6:9], v[102:105], v[62:65]
	ds_read_b128 v[6:9], v245 offset:64
	s_waitcnt lgkmcnt(7)
	v_mfma_f32_16x16x32_bf16 v[62:65], v[10:13], v[106:109], v[62:65]
	ds_read_b128 v[10:13], v245 offset:128
	s_waitcnt lgkmcnt(7)
	v_mfma_f32_16x16x32_bf16 v[62:65], v[14:17], v[110:113], v[62:65]
	ds_read_b128 v[14:17], v245 offset:192
	s_waitcnt lgkmcnt(7)
	v_mfma_f32_16x16x32_bf16 v[62:65], v[18:21], v[114:117], v[62:65]
	ds_read_b128 v[18:21], v245 offset:256
	s_waitcnt lgkmcnt(7)
	v_mfma_f32_16x16x32_bf16 v[62:65], v[22:25], v[118:121], v[62:65]
	ds_read_b128 v[22:25], v245 offset:320
	s_waitcnt lgkmcnt(7)
	v_mfma_f32_16x16x32_bf16 v[62:65], v[26:29], v[122:125], v[62:65]
	ds_read_b128 v[26:29], v245 offset:384
	s_waitcnt lgkmcnt(7)
	v_mfma_f32_16x16x32_bf16 v[62:65], v[30:33], v[224:227], v[62:65]
	ds_read_b128 v[30:33], v245 offset:448
	s_waitcnt lgkmcnt(7)
	v_mfma_f32_16x16x32_bf16 v[66:69], v[2:5], v[98:101], 0
	ds_read_b128 v[2:5], v245 offset:8448
	s_waitcnt lgkmcnt(7)
	v_mfma_f32_16x16x32_bf16 v[66:69], v[6:9], v[102:105], v[66:69]
	ds_read_b128 v[6:9], v245 offset:8512
	s_waitcnt lgkmcnt(7)
	v_mfma_f32_16x16x32_bf16 v[66:69], v[10:13], v[106:109], v[66:69]
	ds_read_b128 v[10:13], v245 offset:8576
	s_waitcnt lgkmcnt(7)
	v_mfma_f32_16x16x32_bf16 v[66:69], v[14:17], v[110:113], v[66:69]
	ds_read_b128 v[14:17], v245 offset:8640
	s_waitcnt lgkmcnt(7)
	v_mfma_f32_16x16x32_bf16 v[66:69], v[18:21], v[114:117], v[66:69]
	ds_read_b128 v[18:21], v245 offset:8704
	s_waitcnt lgkmcnt(7)
	v_mfma_f32_16x16x32_bf16 v[66:69], v[22:25], v[118:121], v[66:69]
	ds_read_b128 v[22:25], v245 offset:8768
	s_waitcnt lgkmcnt(7)
	v_mfma_f32_16x16x32_bf16 v[66:69], v[26:29], v[122:125], v[66:69]
	ds_read_b128 v[26:29], v245 offset:8832
	s_waitcnt lgkmcnt(7)
	v_mfma_f32_16x16x32_bf16 v[66:69], v[30:33], v[224:227], v[66:69]
	ds_read_b128 v[30:33], v245 offset:8896
	s_waitcnt lgkmcnt(7)
	v_mfma_f32_16x16x32_bf16 v[70:73], v[2:5], v[98:101], 0
	ds_read_b128 v[2:5], v245 offset:16896
	s_waitcnt lgkmcnt(7)
	v_mfma_f32_16x16x32_bf16 v[70:73], v[6:9], v[102:105], v[70:73]
	ds_read_b128 v[6:9], v245 offset:16960
	s_waitcnt lgkmcnt(7)
	v_mfma_f32_16x16x32_bf16 v[70:73], v[10:13], v[106:109], v[70:73]
	ds_read_b128 v[10:13], v245 offset:17024
	s_waitcnt lgkmcnt(7)
	v_mfma_f32_16x16x32_bf16 v[70:73], v[14:17], v[110:113], v[70:73]
	ds_read_b128 v[14:17], v245 offset:17088
	s_waitcnt lgkmcnt(7)
	v_mfma_f32_16x16x32_bf16 v[70:73], v[18:21], v[114:117], v[70:73]
	ds_read_b128 v[18:21], v245 offset:17152
	s_waitcnt lgkmcnt(7)
	v_mfma_f32_16x16x32_bf16 v[70:73], v[22:25], v[118:121], v[70:73]
	ds_read_b128 v[22:25], v245 offset:17216
	s_waitcnt lgkmcnt(7)
	v_mfma_f32_16x16x32_bf16 v[70:73], v[26:29], v[122:125], v[70:73]
	ds_read_b128 v[26:29], v245 offset:17280
	s_waitcnt lgkmcnt(7)
	v_mfma_f32_16x16x32_bf16 v[70:73], v[30:33], v[224:227], v[70:73]
	ds_read_b128 v[30:33], v245 offset:17344
	s_waitcnt lgkmcnt(7)
	v_mfma_f32_16x16x32_bf16 v[74:77], v[2:5], v[98:101], 0
	ds_read_b128 v[2:5], v245 offset:25344
	s_waitcnt lgkmcnt(7)
	v_mfma_f32_16x16x32_bf16 v[74:77], v[6:9], v[102:105], v[74:77]
	ds_read_b128 v[6:9], v245 offset:25408
	s_waitcnt lgkmcnt(7)
	v_mfma_f32_16x16x32_bf16 v[74:77], v[10:13], v[106:109], v[74:77]
	ds_read_b128 v[10:13], v245 offset:25472
	s_waitcnt lgkmcnt(7)
	v_mfma_f32_16x16x32_bf16 v[74:77], v[14:17], v[110:113], v[74:77]
	ds_read_b128 v[14:17], v245 offset:25536
	s_waitcnt lgkmcnt(7)
	v_mfma_f32_16x16x32_bf16 v[74:77], v[18:21], v[114:117], v[74:77]
	ds_read_b128 v[18:21], v245 offset:25600
	s_waitcnt lgkmcnt(7)
	v_mfma_f32_16x16x32_bf16 v[74:77], v[22:25], v[118:121], v[74:77]
	ds_read_b128 v[22:25], v245 offset:25664
	s_waitcnt lgkmcnt(7)
	v_mfma_f32_16x16x32_bf16 v[74:77], v[26:29], v[122:125], v[74:77]
	ds_read_b128 v[26:29], v245 offset:25728
	s_waitcnt lgkmcnt(7)
	v_mfma_f32_16x16x32_bf16 v[74:77], v[30:33], v[224:227], v[74:77]
	ds_read_b128 v[30:33], v245 offset:25792
	s_waitcnt lgkmcnt(7)
	v_mfma_f32_16x16x32_bf16 v[78:81], v[2:5], v[98:101], 0
	ds_read_b128 v[2:5], v245 offset:33792
	s_waitcnt lgkmcnt(7)
	v_mfma_f32_16x16x32_bf16 v[78:81], v[6:9], v[102:105], v[78:81]
	ds_read_b128 v[6:9], v245 offset:33856
	s_waitcnt lgkmcnt(7)
	v_mfma_f32_16x16x32_bf16 v[78:81], v[10:13], v[106:109], v[78:81]
	ds_read_b128 v[10:13], v245 offset:33920
	s_waitcnt lgkmcnt(7)
	v_mfma_f32_16x16x32_bf16 v[78:81], v[14:17], v[110:113], v[78:81]
	ds_read_b128 v[14:17], v245 offset:33984
	s_waitcnt lgkmcnt(7)
	v_mfma_f32_16x16x32_bf16 v[78:81], v[18:21], v[114:117], v[78:81]
	ds_read_b128 v[18:21], v245 offset:34048
	s_waitcnt lgkmcnt(7)
	v_mfma_f32_16x16x32_bf16 v[78:81], v[22:25], v[118:121], v[78:81]
	ds_read_b128 v[22:25], v245 offset:34112
	s_waitcnt lgkmcnt(7)
	v_mfma_f32_16x16x32_bf16 v[78:81], v[26:29], v[122:125], v[78:81]
	ds_read_b128 v[26:29], v245 offset:34176
	s_waitcnt lgkmcnt(7)
	v_mfma_f32_16x16x32_bf16 v[78:81], v[30:33], v[224:227], v[78:81]
	ds_read_b128 v[30:33], v245 offset:34240
	s_waitcnt lgkmcnt(7)
	v_mfma_f32_16x16x32_bf16 v[82:85], v[2:5], v[98:101], 0
	ds_read_b128 v[2:5], v245 offset:42240
	s_waitcnt lgkmcnt(7)
	v_mfma_f32_16x16x32_bf16 v[82:85], v[6:9], v[102:105], v[82:85]
	ds_read_b128 v[6:9], v245 offset:42304
	s_waitcnt lgkmcnt(7)
	v_mfma_f32_16x16x32_bf16 v[82:85], v[10:13], v[106:109], v[82:85]
	ds_read_b128 v[10:13], v245 offset:42368
	s_waitcnt lgkmcnt(7)
	v_mfma_f32_16x16x32_bf16 v[82:85], v[14:17], v[110:113], v[82:85]
	ds_read_b128 v[14:17], v245 offset:42432
	s_waitcnt lgkmcnt(7)
	v_mfma_f32_16x16x32_bf16 v[82:85], v[18:21], v[114:117], v[82:85]
	ds_read_b128 v[18:21], v245 offset:42496
	s_waitcnt lgkmcnt(7)
	v_mfma_f32_16x16x32_bf16 v[82:85], v[22:25], v[118:121], v[82:85]
	ds_read_b128 v[22:25], v245 offset:42560
	s_waitcnt lgkmcnt(7)
	v_mfma_f32_16x16x32_bf16 v[82:85], v[26:29], v[122:125], v[82:85]
	ds_read_b128 v[26:29], v245 offset:42624
	s_waitcnt lgkmcnt(7)
	v_mfma_f32_16x16x32_bf16 v[82:85], v[30:33], v[224:227], v[82:85]
	ds_read_b128 v[30:33], v245 offset:42688
	s_waitcnt lgkmcnt(7)
	v_mfma_f32_16x16x32_bf16 v[86:89], v[2:5], v[98:101], 0
	ds_read_b128 v[2:5], v245 offset:50688
	s_waitcnt lgkmcnt(7)
	v_mfma_f32_16x16x32_bf16 v[86:89], v[6:9], v[102:105], v[86:89]
	ds_read_b128 v[6:9], v245 offset:50752
	s_waitcnt lgkmcnt(7)
	v_mfma_f32_16x16x32_bf16 v[86:89], v[10:13], v[106:109], v[86:89]
	ds_read_b128 v[10:13], v245 offset:50816
	s_waitcnt lgkmcnt(7)
	v_mfma_f32_16x16x32_bf16 v[86:89], v[14:17], v[110:113], v[86:89]
	ds_read_b128 v[14:17], v245 offset:50880
	s_waitcnt lgkmcnt(7)
	v_mfma_f32_16x16x32_bf16 v[86:89], v[18:21], v[114:117], v[86:89]
	ds_read_b128 v[18:21], v245 offset:50944
	s_waitcnt lgkmcnt(7)
	v_mfma_f32_16x16x32_bf16 v[86:89], v[22:25], v[118:121], v[86:89]
	ds_read_b128 v[22:25], v245 offset:51008
	s_waitcnt lgkmcnt(7)
	v_mfma_f32_16x16x32_bf16 v[86:89], v[26:29], v[122:125], v[86:89]
	ds_read_b128 v[26:29], v245 offset:51072
	s_waitcnt lgkmcnt(7)
	v_mfma_f32_16x16x32_bf16 v[86:89], v[30:33], v[224:227], v[86:89]
	ds_read_b128 v[30:33], v245 offset:51136
	s_waitcnt lgkmcnt(7)
	v_mfma_f32_16x16x32_bf16 v[90:93], v[2:5], v[98:101], 0
	ds_read_b128 v[2:5], v245 offset:59136
	s_waitcnt lgkmcnt(7)
	v_mfma_f32_16x16x32_bf16 v[90:93], v[6:9], v[102:105], v[90:93]
	ds_read_b128 v[6:9], v245 offset:59200
	s_waitcnt lgkmcnt(7)
	v_mfma_f32_16x16x32_bf16 v[90:93], v[10:13], v[106:109], v[90:93]
	ds_read_b128 v[10:13], v245 offset:59264
	s_waitcnt lgkmcnt(7)
	v_mfma_f32_16x16x32_bf16 v[90:93], v[14:17], v[110:113], v[90:93]
	ds_read_b128 v[14:17], v245 offset:59328
	s_waitcnt lgkmcnt(7)
	v_mfma_f32_16x16x32_bf16 v[90:93], v[18:21], v[114:117], v[90:93]
	ds_read_b128 v[18:21], v245 offset:59392
	s_waitcnt lgkmcnt(7)
	v_mfma_f32_16x16x32_bf16 v[90:93], v[22:25], v[118:121], v[90:93]
	ds_read_b128 v[22:25], v245 offset:59456
	s_waitcnt lgkmcnt(7)
	v_mfma_f32_16x16x32_bf16 v[90:93], v[26:29], v[122:125], v[90:93]
	ds_read_b128 v[26:29], v245 offset:59520
	s_waitcnt lgkmcnt(7)
	v_mfma_f32_16x16x32_bf16 v[90:93], v[30:33], v[224:227], v[90:93]
	ds_read_b128 v[30:33], v245 offset:59584
	s_waitcnt lgkmcnt(7)
	v_mfma_f32_16x16x32_bf16 v[94:97], v[2:5], v[98:101], 0
	s_waitcnt lgkmcnt(6)
	v_mfma_f32_16x16x32_bf16 v[94:97], v[6:9], v[102:105], v[94:97]
	s_waitcnt lgkmcnt(5)
	v_mfma_f32_16x16x32_bf16 v[94:97], v[10:13], v[106:109], v[94:97]
	s_waitcnt lgkmcnt(4)
	v_mfma_f32_16x16x32_bf16 v[94:97], v[14:17], v[110:113], v[94:97]
	s_waitcnt lgkmcnt(3)
	v_mfma_f32_16x16x32_bf16 v[94:97], v[18:21], v[114:117], v[94:97]
	s_waitcnt lgkmcnt(2)
	v_mfma_f32_16x16x32_bf16 v[94:97], v[22:25], v[118:121], v[94:97]
	s_waitcnt lgkmcnt(1)
	v_mfma_f32_16x16x32_bf16 v[94:97], v[26:29], v[122:125], v[94:97]
	s_waitcnt lgkmcnt(0)
	v_mfma_f32_16x16x32_bf16 v[94:97], v[30:33], v[224:227], v[94:97]
	global_load_dwordx4 v[98:101], v[246:247], off
	global_load_dwordx4 v[102:105], v[246:247], off offset:64
	global_load_dwordx4 v[106:109], v[246:247], off offset:128
	global_load_dwordx4 v[110:113], v[246:247], off offset:192
	global_load_dwordx4 v[114:117], v[246:247], off offset:256
	global_load_dwordx4 v[118:121], v[246:247], off offset:320
	global_load_dwordx4 v[122:125], v[246:247], off offset:384
	global_load_dwordx4 v[224:227], v[246:247], off offset:448
	v_max3_f32 v248, v34, v35, v205
	v_max3_f32 v248, v248, v36, v37
	v_max3_f32 v248, v248, v38, v39
	v_max3_f32 v248, v248, v40, v41
	v_max3_f32 v248, v248, v42, v43
	v_max3_f32 v248, v248, v44, v45
	v_max3_f32 v248, v248, v46, v47
	v_max3_f32 v248, v248, v48, v49
	v_max3_f32 v248, v248, v50, v51
	v_max3_f32 v248, v248, v52, v53
	v_max3_f32 v248, v248, v54, v55
	v_max3_f32 v248, v248, v56, v57
	v_max3_f32 v248, v248, v58, v59
	v_max3_f32 v248, v248, v60, v61
	v_max3_f32 v248, v248, v62, v63
	v_max3_f32 v248, v248, v64, v65
	v_max3_f32 v248, v248, v66, v67
	v_max3_f32 v248, v248, v68, v69
	v_max3_f32 v248, v248, v70, v71
	v_max3_f32 v248, v248, v72, v73
	v_max3_f32 v248, v248, v74, v75
	v_max3_f32 v248, v248, v76, v77
	v_max3_f32 v248, v248, v78, v79
	v_max3_f32 v248, v248, v80, v81
	v_max3_f32 v248, v248, v82, v83
	v_max3_f32 v248, v248, v84, v85
	v_max3_f32 v248, v248, v86, v87
	v_max3_f32 v248, v248, v88, v89
	v_max3_f32 v248, v248, v90, v91
	v_max3_f32 v248, v248, v92, v93
	v_max3_f32 v248, v248, v94, v95
	v_max3_f32 v248, v248, v96, v97
	v_xor_b32_e32 v228, 16, v195
	v_lshlrev_b32_e32 v228, 2, v228
	ds_bpermute_b32 v228, v228, v248
	s_waitcnt lgkmcnt(0)
	v_max_f32_e32 v248, v248, v228
	v_xor_b32_e32 v228, 32, v195
	v_lshlrev_b32_e32 v228, 2, v228
	ds_bpermute_b32 v228, v228, v248
	s_waitcnt lgkmcnt(0)
	v_max_f32_e32 v248, v248, v228
	v_mul_f32_e32 v248, 0xbdb8aa3b, v248
	v_fmamk_f32 v34, v34, 0x3db8aa3b, v248
	v_fmamk_f32 v35, v35, 0x3db8aa3b, v248
	v_fmamk_f32 v36, v36, 0x3db8aa3b, v248
	v_fmamk_f32 v37, v37, 0x3db8aa3b, v248
	v_exp_f32_e32 v34, v34
	v_exp_f32_e32 v35, v35
	v_exp_f32_e32 v36, v36
	v_exp_f32_e32 v37, v37
	v_fmamk_f32 v38, v38, 0x3db8aa3b, v248
	v_fmamk_f32 v39, v39, 0x3db8aa3b, v248
	v_fmamk_f32 v40, v40, 0x3db8aa3b, v248
	v_fmamk_f32 v41, v41, 0x3db8aa3b, v248
	v_exp_f32_e32 v38, v38
	v_exp_f32_e32 v39, v39
	v_exp_f32_e32 v40, v40
	v_exp_f32_e32 v41, v41
	v_add_f32_e32 v249, 0, v34
	v_add_f32_e32 v249, v249, v35
	v_add_f32_e32 v249, v249, v36
	v_add_f32_e32 v249, v249, v37
	v_fmamk_f32 v42, v42, 0x3db8aa3b, v248
	v_fmamk_f32 v43, v43, 0x3db8aa3b, v248
	v_fmamk_f32 v44, v44, 0x3db8aa3b, v248
	v_fmamk_f32 v45, v45, 0x3db8aa3b, v248
	v_exp_f32_e32 v42, v42
	v_exp_f32_e32 v43, v43
	v_exp_f32_e32 v44, v44
	v_exp_f32_e32 v45, v45
	v_add_f32_e32 v249, v249, v38
	v_add_f32_e32 v249, v249, v39
	v_add_f32_e32 v249, v249, v40
	v_add_f32_e32 v249, v249, v41
	v_fmamk_f32 v46, v46, 0x3db8aa3b, v248
	v_fmamk_f32 v47, v47, 0x3db8aa3b, v248
	v_fmamk_f32 v48, v48, 0x3db8aa3b, v248
	v_fmamk_f32 v49, v49, 0x3db8aa3b, v248
	v_exp_f32_e32 v46, v46
	v_exp_f32_e32 v47, v47
	v_exp_f32_e32 v48, v48
	v_exp_f32_e32 v49, v49
	v_add_f32_e32 v249, v249, v42
	v_add_f32_e32 v249, v249, v43
	v_add_f32_e32 v249, v249, v44
	v_add_f32_e32 v249, v249, v45
	v_fmamk_f32 v50, v50, 0x3db8aa3b, v248
	v_fmamk_f32 v51, v51, 0x3db8aa3b, v248
	v_fmamk_f32 v52, v52, 0x3db8aa3b, v248
	v_fmamk_f32 v53, v53, 0x3db8aa3b, v248
	v_exp_f32_e32 v50, v50
	v_exp_f32_e32 v51, v51
	v_exp_f32_e32 v52, v52
	v_exp_f32_e32 v53, v53
	v_add_f32_e32 v249, v249, v46
	v_add_f32_e32 v249, v249, v47
	v_add_f32_e32 v249, v249, v48
	v_add_f32_e32 v249, v249, v49
	v_fmamk_f32 v54, v54, 0x3db8aa3b, v248
	v_fmamk_f32 v55, v55, 0x3db8aa3b, v248
	v_fmamk_f32 v56, v56, 0x3db8aa3b, v248
	v_fmamk_f32 v57, v57, 0x3db8aa3b, v248
	v_exp_f32_e32 v54, v54
	v_exp_f32_e32 v55, v55
	v_exp_f32_e32 v56, v56
	v_exp_f32_e32 v57, v57
	v_add_f32_e32 v249, v249, v50
	v_add_f32_e32 v249, v249, v51
	v_add_f32_e32 v249, v249, v52
	v_add_f32_e32 v249, v249, v53
	v_fmamk_f32 v58, v58, 0x3db8aa3b, v248
	v_fmamk_f32 v59, v59, 0x3db8aa3b, v248
	v_fmamk_f32 v60, v60, 0x3db8aa3b, v248
	v_fmamk_f32 v61, v61, 0x3db8aa3b, v248
	v_exp_f32_e32 v58, v58
	v_exp_f32_e32 v59, v59
	v_exp_f32_e32 v60, v60
	v_exp_f32_e32 v61, v61
	v_add_f32_e32 v249, v249, v54
	v_add_f32_e32 v249, v249, v55
	v_add_f32_e32 v249, v249, v56
	v_add_f32_e32 v249, v249, v57
	v_fmamk_f32 v62, v62, 0x3db8aa3b, v248
	v_fmamk_f32 v63, v63, 0x3db8aa3b, v248
	v_fmamk_f32 v64, v64, 0x3db8aa3b, v248
	v_fmamk_f32 v65, v65, 0x3db8aa3b, v248
	v_exp_f32_e32 v62, v62
	v_exp_f32_e32 v63, v63
	v_exp_f32_e32 v64, v64
	v_exp_f32_e32 v65, v65
	v_add_f32_e32 v249, v249, v58
	v_add_f32_e32 v249, v249, v59
	v_add_f32_e32 v249, v249, v60
	v_add_f32_e32 v249, v249, v61
	v_fmamk_f32 v66, v66, 0x3db8aa3b, v248
	v_fmamk_f32 v67, v67, 0x3db8aa3b, v248
	v_fmamk_f32 v68, v68, 0x3db8aa3b, v248
	v_fmamk_f32 v69, v69, 0x3db8aa3b, v248
	v_exp_f32_e32 v66, v66
	v_exp_f32_e32 v67, v67
	v_exp_f32_e32 v68, v68
	v_exp_f32_e32 v69, v69
	v_add_f32_e32 v249, v249, v62
	v_add_f32_e32 v249, v249, v63
	v_add_f32_e32 v249, v249, v64
	v_add_f32_e32 v249, v249, v65
	v_fmamk_f32 v70, v70, 0x3db8aa3b, v248
	v_fmamk_f32 v71, v71, 0x3db8aa3b, v248
	v_fmamk_f32 v72, v72, 0x3db8aa3b, v248
	v_fmamk_f32 v73, v73, 0x3db8aa3b, v248
	v_exp_f32_e32 v70, v70
	v_exp_f32_e32 v71, v71
	v_exp_f32_e32 v72, v72
	v_exp_f32_e32 v73, v73
	v_add_f32_e32 v249, v249, v66
	v_add_f32_e32 v249, v249, v67
	v_add_f32_e32 v249, v249, v68
	v_add_f32_e32 v249, v249, v69
	v_fmamk_f32 v74, v74, 0x3db8aa3b, v248
	v_fmamk_f32 v75, v75, 0x3db8aa3b, v248
	v_fmamk_f32 v76, v76, 0x3db8aa3b, v248
	v_fmamk_f32 v77, v77, 0x3db8aa3b, v248
	v_exp_f32_e32 v74, v74
	v_exp_f32_e32 v75, v75
	v_exp_f32_e32 v76, v76
	v_exp_f32_e32 v77, v77
	v_add_f32_e32 v249, v249, v70
	v_add_f32_e32 v249, v249, v71
	v_add_f32_e32 v249, v249, v72
	v_add_f32_e32 v249, v249, v73
	v_fmamk_f32 v78, v78, 0x3db8aa3b, v248
	v_fmamk_f32 v79, v79, 0x3db8aa3b, v248
	v_fmamk_f32 v80, v80, 0x3db8aa3b, v248
	v_fmamk_f32 v81, v81, 0x3db8aa3b, v248
	v_exp_f32_e32 v78, v78
	v_exp_f32_e32 v79, v79
	v_exp_f32_e32 v80, v80
	v_exp_f32_e32 v81, v81
	v_add_f32_e32 v249, v249, v74
	v_add_f32_e32 v249, v249, v75
	v_add_f32_e32 v249, v249, v76
	v_add_f32_e32 v249, v249, v77
	v_fmamk_f32 v82, v82, 0x3db8aa3b, v248
	v_fmamk_f32 v83, v83, 0x3db8aa3b, v248
	v_fmamk_f32 v84, v84, 0x3db8aa3b, v248
	v_fmamk_f32 v85, v85, 0x3db8aa3b, v248
	v_exp_f32_e32 v82, v82
	v_exp_f32_e32 v83, v83
	v_exp_f32_e32 v84, v84
	v_exp_f32_e32 v85, v85
	v_add_f32_e32 v249, v249, v78
	v_add_f32_e32 v249, v249, v79
	v_add_f32_e32 v249, v249, v80
	v_add_f32_e32 v249, v249, v81
	v_fmamk_f32 v86, v86, 0x3db8aa3b, v248
	v_fmamk_f32 v87, v87, 0x3db8aa3b, v248
	v_fmamk_f32 v88, v88, 0x3db8aa3b, v248
	v_fmamk_f32 v89, v89, 0x3db8aa3b, v248
	v_exp_f32_e32 v86, v86
	v_exp_f32_e32 v87, v87
	v_exp_f32_e32 v88, v88
	v_exp_f32_e32 v89, v89
	v_add_f32_e32 v249, v249, v82
	v_add_f32_e32 v249, v249, v83
	v_add_f32_e32 v249, v249, v84
	v_add_f32_e32 v249, v249, v85
	v_fmamk_f32 v90, v90, 0x3db8aa3b, v248
	v_fmamk_f32 v91, v91, 0x3db8aa3b, v248
	v_fmamk_f32 v92, v92, 0x3db8aa3b, v248
	v_fmamk_f32 v93, v93, 0x3db8aa3b, v248
	v_exp_f32_e32 v90, v90
	v_exp_f32_e32 v91, v91
	v_exp_f32_e32 v92, v92
	v_exp_f32_e32 v93, v93
	v_add_f32_e32 v249, v249, v86
	v_add_f32_e32 v249, v249, v87
	v_add_f32_e32 v249, v249, v88
	v_add_f32_e32 v249, v249, v89
	v_fmamk_f32 v94, v94, 0x3db8aa3b, v248
	v_fmamk_f32 v95, v95, 0x3db8aa3b, v248
	v_fmamk_f32 v96, v96, 0x3db8aa3b, v248
	v_fmamk_f32 v97, v97, 0x3db8aa3b, v248
	v_exp_f32_e32 v94, v94
	v_exp_f32_e32 v95, v95
	v_exp_f32_e32 v96, v96
	v_exp_f32_e32 v97, v97
	v_add_f32_e32 v249, v249, v90
	v_add_f32_e32 v249, v249, v91
	v_add_f32_e32 v249, v249, v92
	v_add_f32_e32 v249, v249, v93
	s_nop 0
	v_add_f32_e32 v249, v249, v94
	v_add_f32_e32 v249, v249, v95
	v_add_f32_e32 v249, v249, v96
	v_add_f32_e32 v249, v249, v97
	v_xor_b32_e32 v228, 16, v195
	v_lshlrev_b32_e32 v228, 2, v228
	ds_bpermute_b32 v228, v228, v249
	s_waitcnt lgkmcnt(0)
	v_add_f32_e32 v249, v249, v228
	v_xor_b32_e32 v228, 32, v195
	v_lshlrev_b32_e32 v228, 2, v228
	ds_bpermute_b32 v228, v228, v249
	s_waitcnt lgkmcnt(0)
	v_add_f32_e32 v249, v249, v228
	v_rcp_f32_e32 v134, v249
	v_cvt_pk_bf16_f32 v2, v34, v35
	v_cvt_pk_bf16_f32 v3, v36, v37
	v_cvt_pk_bf16_f32 v4, v38, v39
	v_cvt_pk_bf16_f32 v5, v40, v41
	v_cvt_pk_bf16_f32 v6, v42, v43
	v_cvt_pk_bf16_f32 v7, v44, v45
	v_cvt_pk_bf16_f32 v8, v46, v47
	v_cvt_pk_bf16_f32 v9, v48, v49
	v_cvt_pk_bf16_f32 v10, v50, v51
	v_cvt_pk_bf16_f32 v11, v52, v53
	v_cvt_pk_bf16_f32 v12, v54, v55
	v_cvt_pk_bf16_f32 v13, v56, v57
	v_cvt_pk_bf16_f32 v14, v58, v59
	v_cvt_pk_bf16_f32 v15, v60, v61
	v_cvt_pk_bf16_f32 v16, v62, v63
	v_cvt_pk_bf16_f32 v17, v64, v65
	v_cvt_pk_bf16_f32 v18, v66, v67
	v_cvt_pk_bf16_f32 v19, v68, v69
	v_cvt_pk_bf16_f32 v20, v70, v71
	v_cvt_pk_bf16_f32 v21, v72, v73
	v_cvt_pk_bf16_f32 v22, v74, v75
	v_cvt_pk_bf16_f32 v23, v76, v77
	v_cvt_pk_bf16_f32 v24, v78, v79
	v_cvt_pk_bf16_f32 v25, v80, v81
	v_cvt_pk_bf16_f32 v26, v82, v83
	v_cvt_pk_bf16_f32 v27, v84, v85
	v_cvt_pk_bf16_f32 v28, v86, v87
	v_cvt_pk_bf16_f32 v29, v88, v89
	v_cvt_pk_bf16_f32 v30, v90, v91
	v_cvt_pk_bf16_f32 v31, v92, v93
	v_cvt_pk_bf16_f32 v32, v94, v95
	v_cvt_pk_bf16_f32 v33, v96, v97
	s_waitcnt vmcnt(0)
	ds_read_b128 v[228:231], v244
	ds_read_b128 v[232:235], v244 offset:64
	ds_read_b128 v[236:239], v244 offset:128
	ds_read_b128 v[240:243], v244 offset:192
	s_waitcnt lgkmcnt(3)
	v_mfma_f32_16x16x32_bf16 v[34:37], v[228:231], v[98:101], 0
	ds_read_b128 v[228:231], v244 offset:256
	s_waitcnt lgkmcnt(3)
	v_mfma_f32_16x16x32_bf16 v[34:37], v[232:235], v[102:105], v[34:37]
	ds_read_b128 v[232:235], v244 offset:320
	s_waitcnt lgkmcnt(3)
	v_mfma_f32_16x16x32_bf16 v[34:37], v[236:239], v[106:109], v[34:37]
	ds_read_b128 v[236:239], v244 offset:384
	s_waitcnt lgkmcnt(3)
	v_mfma_f32_16x16x32_bf16 v[34:37], v[240:243], v[110:113], v[34:37]
	ds_read_b128 v[240:243], v244 offset:448
	s_waitcnt lgkmcnt(3)
	v_mfma_f32_16x16x32_bf16 v[34:37], v[228:231], v[114:117], v[34:37]
	ds_read_b128 v[228:231], v244 offset:8448
	s_waitcnt lgkmcnt(3)
	v_mfma_f32_16x16x32_bf16 v[34:37], v[232:235], v[118:121], v[34:37]
	ds_read_b128 v[232:235], v244 offset:8512
	s_waitcnt lgkmcnt(3)
	v_mfma_f32_16x16x32_bf16 v[34:37], v[236:239], v[122:125], v[34:37]
	ds_read_b128 v[236:239], v244 offset:8576
	s_waitcnt lgkmcnt(3)
	v_mfma_f32_16x16x32_bf16 v[34:37], v[240:243], v[224:227], v[34:37]
	ds_read_b128 v[240:243], v244 offset:8640
	s_waitcnt lgkmcnt(3)
	v_mfma_f32_16x16x32_bf16 v[38:41], v[228:231], v[98:101], 0
	ds_read_b128 v[228:231], v244 offset:8704
	s_waitcnt lgkmcnt(3)
	v_mfma_f32_16x16x32_bf16 v[38:41], v[232:235], v[102:105], v[38:41]
	ds_read_b128 v[232:235], v244 offset:8768
	s_waitcnt lgkmcnt(3)
	v_mfma_f32_16x16x32_bf16 v[38:41], v[236:239], v[106:109], v[38:41]
	ds_read_b128 v[236:239], v244 offset:8832
	s_waitcnt lgkmcnt(3)
	v_mfma_f32_16x16x32_bf16 v[38:41], v[240:243], v[110:113], v[38:41]
	ds_read_b128 v[240:243], v244 offset:8896
	s_waitcnt lgkmcnt(3)
	v_mfma_f32_16x16x32_bf16 v[38:41], v[228:231], v[114:117], v[38:41]
	ds_read_b128 v[228:231], v244 offset:16896
	s_waitcnt lgkmcnt(3)
	v_mfma_f32_16x16x32_bf16 v[38:41], v[232:235], v[118:121], v[38:41]
	ds_read_b128 v[232:235], v244 offset:16960
	s_waitcnt lgkmcnt(3)
	v_mfma_f32_16x16x32_bf16 v[38:41], v[236:239], v[122:125], v[38:41]
	ds_read_b128 v[236:239], v244 offset:17024
	s_waitcnt lgkmcnt(3)
	v_mfma_f32_16x16x32_bf16 v[38:41], v[240:243], v[224:227], v[38:41]
	ds_read_b128 v[240:243], v244 offset:17088
	s_waitcnt lgkmcnt(3)
	v_mfma_f32_16x16x32_bf16 v[42:45], v[228:231], v[98:101], 0
	ds_read_b128 v[228:231], v244 offset:17152
	s_waitcnt lgkmcnt(3)
	v_mfma_f32_16x16x32_bf16 v[42:45], v[232:235], v[102:105], v[42:45]
	ds_read_b128 v[232:235], v244 offset:17216
	s_waitcnt lgkmcnt(3)
	v_mfma_f32_16x16x32_bf16 v[42:45], v[236:239], v[106:109], v[42:45]
	ds_read_b128 v[236:239], v244 offset:17280
	s_waitcnt lgkmcnt(3)
	v_mfma_f32_16x16x32_bf16 v[42:45], v[240:243], v[110:113], v[42:45]
	ds_read_b128 v[240:243], v244 offset:17344
	s_waitcnt lgkmcnt(3)
	v_mfma_f32_16x16x32_bf16 v[42:45], v[228:231], v[114:117], v[42:45]
	ds_read_b128 v[228:231], v244 offset:25344
	s_waitcnt lgkmcnt(3)
	v_mfma_f32_16x16x32_bf16 v[42:45], v[232:235], v[118:121], v[42:45]
	ds_read_b128 v[232:235], v244 offset:25408
	s_waitcnt lgkmcnt(3)
	v_mfma_f32_16x16x32_bf16 v[42:45], v[236:239], v[122:125], v[42:45]
	ds_read_b128 v[236:239], v244 offset:25472
	s_waitcnt lgkmcnt(3)
	v_mfma_f32_16x16x32_bf16 v[42:45], v[240:243], v[224:227], v[42:45]
	ds_read_b128 v[240:243], v244 offset:25536
	s_waitcnt lgkmcnt(3)
	v_mfma_f32_16x16x32_bf16 v[46:49], v[228:231], v[98:101], 0
	ds_read_b128 v[228:231], v244 offset:25600
	s_waitcnt lgkmcnt(3)
	v_mfma_f32_16x16x32_bf16 v[46:49], v[232:235], v[102:105], v[46:49]
	ds_read_b128 v[232:235], v244 offset:25664
	s_waitcnt lgkmcnt(3)
	v_mfma_f32_16x16x32_bf16 v[46:49], v[236:239], v[106:109], v[46:49]
	ds_read_b128 v[236:239], v244 offset:25728
	s_waitcnt lgkmcnt(3)
	v_mfma_f32_16x16x32_bf16 v[46:49], v[240:243], v[110:113], v[46:49]
	ds_read_b128 v[240:243], v244 offset:25792
	s_waitcnt lgkmcnt(3)
	v_mfma_f32_16x16x32_bf16 v[46:49], v[228:231], v[114:117], v[46:49]
	ds_read_b128 v[228:231], v244 offset:33792
	s_waitcnt lgkmcnt(3)
	v_mfma_f32_16x16x32_bf16 v[46:49], v[232:235], v[118:121], v[46:49]
	ds_read_b128 v[232:235], v244 offset:33856
	s_waitcnt lgkmcnt(3)
	v_mfma_f32_16x16x32_bf16 v[46:49], v[236:239], v[122:125], v[46:49]
	ds_read_b128 v[236:239], v244 offset:33920
	s_waitcnt lgkmcnt(3)
	v_mfma_f32_16x16x32_bf16 v[46:49], v[240:243], v[224:227], v[46:49]
	ds_read_b128 v[240:243], v244 offset:33984
	s_waitcnt lgkmcnt(3)
	v_mfma_f32_16x16x32_bf16 v[50:53], v[228:231], v[98:101], 0
	ds_read_b128 v[228:231], v244 offset:34048
	s_waitcnt lgkmcnt(3)
	v_mfma_f32_16x16x32_bf16 v[50:53], v[232:235], v[102:105], v[50:53]
	ds_read_b128 v[232:235], v244 offset:34112
	s_waitcnt lgkmcnt(3)
	v_mfma_f32_16x16x32_bf16 v[50:53], v[236:239], v[106:109], v[50:53]
	ds_read_b128 v[236:239], v244 offset:34176
	s_waitcnt lgkmcnt(3)
	v_mfma_f32_16x16x32_bf16 v[50:53], v[240:243], v[110:113], v[50:53]
	ds_read_b128 v[240:243], v244 offset:34240
	s_waitcnt lgkmcnt(3)
	v_mfma_f32_16x16x32_bf16 v[50:53], v[228:231], v[114:117], v[50:53]
	ds_read_b128 v[228:231], v244 offset:42240
	s_waitcnt lgkmcnt(3)
	v_mfma_f32_16x16x32_bf16 v[50:53], v[232:235], v[118:121], v[50:53]
	ds_read_b128 v[232:235], v244 offset:42304
	s_waitcnt lgkmcnt(3)
	v_mfma_f32_16x16x32_bf16 v[50:53], v[236:239], v[122:125], v[50:53]
	ds_read_b128 v[236:239], v244 offset:42368
	s_waitcnt lgkmcnt(3)
	v_mfma_f32_16x16x32_bf16 v[50:53], v[240:243], v[224:227], v[50:53]
	ds_read_b128 v[240:243], v244 offset:42432
	s_waitcnt lgkmcnt(3)
	v_mfma_f32_16x16x32_bf16 v[54:57], v[228:231], v[98:101], 0
	ds_read_b128 v[228:231], v244 offset:42496
	s_waitcnt lgkmcnt(3)
	v_mfma_f32_16x16x32_bf16 v[54:57], v[232:235], v[102:105], v[54:57]
	ds_read_b128 v[232:235], v244 offset:42560
	s_waitcnt lgkmcnt(3)
	v_mfma_f32_16x16x32_bf16 v[54:57], v[236:239], v[106:109], v[54:57]
	ds_read_b128 v[236:239], v244 offset:42624
	s_waitcnt lgkmcnt(3)
	v_mfma_f32_16x16x32_bf16 v[54:57], v[240:243], v[110:113], v[54:57]
	ds_read_b128 v[240:243], v244 offset:42688
	s_waitcnt lgkmcnt(3)
	v_mfma_f32_16x16x32_bf16 v[54:57], v[228:231], v[114:117], v[54:57]
	ds_read_b128 v[228:231], v244 offset:50688
	s_waitcnt lgkmcnt(3)
	v_mfma_f32_16x16x32_bf16 v[54:57], v[232:235], v[118:121], v[54:57]
	ds_read_b128 v[232:235], v244 offset:50752
	s_waitcnt lgkmcnt(3)
	v_mfma_f32_16x16x32_bf16 v[54:57], v[236:239], v[122:125], v[54:57]
	ds_read_b128 v[236:239], v244 offset:50816
	s_waitcnt lgkmcnt(3)
	v_mfma_f32_16x16x32_bf16 v[54:57], v[240:243], v[224:227], v[54:57]
	ds_read_b128 v[240:243], v244 offset:50880
	s_waitcnt lgkmcnt(3)
	v_mfma_f32_16x16x32_bf16 v[58:61], v[228:231], v[98:101], 0
	ds_read_b128 v[228:231], v244 offset:50944
	s_waitcnt lgkmcnt(3)
	v_mfma_f32_16x16x32_bf16 v[58:61], v[232:235], v[102:105], v[58:61]
	ds_read_b128 v[232:235], v244 offset:51008
	s_waitcnt lgkmcnt(3)
	v_mfma_f32_16x16x32_bf16 v[58:61], v[236:239], v[106:109], v[58:61]
	ds_read_b128 v[236:239], v244 offset:51072
	s_waitcnt lgkmcnt(3)
	v_mfma_f32_16x16x32_bf16 v[58:61], v[240:243], v[110:113], v[58:61]
	ds_read_b128 v[240:243], v244 offset:51136
	s_waitcnt lgkmcnt(3)
	v_mfma_f32_16x16x32_bf16 v[58:61], v[228:231], v[114:117], v[58:61]
	ds_read_b128 v[228:231], v244 offset:59136
	s_waitcnt lgkmcnt(3)
	v_mfma_f32_16x16x32_bf16 v[58:61], v[232:235], v[118:121], v[58:61]
	ds_read_b128 v[232:235], v244 offset:59200
	s_waitcnt lgkmcnt(3)
	v_mfma_f32_16x16x32_bf16 v[58:61], v[236:239], v[122:125], v[58:61]
	ds_read_b128 v[236:239], v244 offset:59264
	s_waitcnt lgkmcnt(3)
	v_mfma_f32_16x16x32_bf16 v[58:61], v[240:243], v[224:227], v[58:61]
	ds_read_b128 v[240:243], v244 offset:59328
	s_waitcnt lgkmcnt(3)
	v_mfma_f32_16x16x32_bf16 v[62:65], v[228:231], v[98:101], 0
	ds_read_b128 v[228:231], v244 offset:59392
	s_waitcnt lgkmcnt(3)
	v_mfma_f32_16x16x32_bf16 v[62:65], v[232:235], v[102:105], v[62:65]
	ds_read_b128 v[232:235], v244 offset:59456
	s_waitcnt lgkmcnt(3)
	v_mfma_f32_16x16x32_bf16 v[62:65], v[236:239], v[106:109], v[62:65]
	ds_read_b128 v[236:239], v244 offset:59520
	s_waitcnt lgkmcnt(3)
	v_mfma_f32_16x16x32_bf16 v[62:65], v[240:243], v[110:113], v[62:65]
	ds_read_b128 v[240:243], v244 offset:59584
	s_waitcnt lgkmcnt(3)
	v_mfma_f32_16x16x32_bf16 v[62:65], v[228:231], v[114:117], v[62:65]
	ds_read_b128 v[228:231], v245
	s_waitcnt lgkmcnt(3)
	v_mfma_f32_16x16x32_bf16 v[62:65], v[232:235], v[118:121], v[62:65]
	ds_read_b128 v[232:235], v245 offset:64
	s_waitcnt lgkmcnt(3)
	v_mfma_f32_16x16x32_bf16 v[62:65], v[236:239], v[122:125], v[62:65]
	ds_read_b128 v[236:239], v245 offset:128
	s_waitcnt lgkmcnt(3)
	v_mfma_f32_16x16x32_bf16 v[62:65], v[240:243], v[224:227], v[62:65]
	ds_read_b128 v[240:243], v245 offset:192
	s_waitcnt lgkmcnt(3)
	v_mfma_f32_16x16x32_bf16 v[66:69], v[228:231], v[98:101], 0
	ds_read_b128 v[228:231], v245 offset:256
	s_waitcnt lgkmcnt(3)
	v_mfma_f32_16x16x32_bf16 v[66:69], v[232:235], v[102:105], v[66:69]
	ds_read_b128 v[232:235], v245 offset:320
	s_waitcnt lgkmcnt(3)
	v_mfma_f32_16x16x32_bf16 v[66:69], v[236:239], v[106:109], v[66:69]
	ds_read_b128 v[236:239], v245 offset:384
	s_waitcnt lgkmcnt(3)
	v_mfma_f32_16x16x32_bf16 v[66:69], v[240:243], v[110:113], v[66:69]
	ds_read_b128 v[240:243], v245 offset:448
	s_waitcnt lgkmcnt(3)
	v_mfma_f32_16x16x32_bf16 v[66:69], v[228:231], v[114:117], v[66:69]
	ds_read_b128 v[228:231], v245 offset:8448
	s_waitcnt lgkmcnt(3)
	v_mfma_f32_16x16x32_bf16 v[66:69], v[232:235], v[118:121], v[66:69]
	ds_read_b128 v[232:235], v245 offset:8512
	s_waitcnt lgkmcnt(3)
	v_mfma_f32_16x16x32_bf16 v[66:69], v[236:239], v[122:125], v[66:69]
	ds_read_b128 v[236:239], v245 offset:8576
	s_waitcnt lgkmcnt(3)
	v_mfma_f32_16x16x32_bf16 v[66:69], v[240:243], v[224:227], v[66:69]
	ds_read_b128 v[240:243], v245 offset:8640
	s_waitcnt lgkmcnt(3)
	v_mfma_f32_16x16x32_bf16 v[70:73], v[228:231], v[98:101], 0
	ds_read_b128 v[228:231], v245 offset:8704
	s_waitcnt lgkmcnt(3)
	v_mfma_f32_16x16x32_bf16 v[70:73], v[232:235], v[102:105], v[70:73]
	ds_read_b128 v[232:235], v245 offset:8768
	s_waitcnt lgkmcnt(3)
	v_mfma_f32_16x16x32_bf16 v[70:73], v[236:239], v[106:109], v[70:73]
	ds_read_b128 v[236:239], v245 offset:8832
	s_waitcnt lgkmcnt(3)
	v_mfma_f32_16x16x32_bf16 v[70:73], v[240:243], v[110:113], v[70:73]
	ds_read_b128 v[240:243], v245 offset:8896
	s_waitcnt lgkmcnt(3)
	v_mfma_f32_16x16x32_bf16 v[70:73], v[228:231], v[114:117], v[70:73]
	ds_read_b128 v[228:231], v245 offset:16896
	s_waitcnt lgkmcnt(3)
	v_mfma_f32_16x16x32_bf16 v[70:73], v[232:235], v[118:121], v[70:73]
	ds_read_b128 v[232:235], v245 offset:16960
	s_waitcnt lgkmcnt(3)
	v_mfma_f32_16x16x32_bf16 v[70:73], v[236:239], v[122:125], v[70:73]
	ds_read_b128 v[236:239], v245 offset:17024
	s_waitcnt lgkmcnt(3)
	v_mfma_f32_16x16x32_bf16 v[70:73], v[240:243], v[224:227], v[70:73]
	ds_read_b128 v[240:243], v245 offset:17088
	s_waitcnt lgkmcnt(3)
	v_mfma_f32_16x16x32_bf16 v[74:77], v[228:231], v[98:101], 0
	ds_read_b128 v[228:231], v245 offset:17152
	s_waitcnt lgkmcnt(3)
	v_mfma_f32_16x16x32_bf16 v[74:77], v[232:235], v[102:105], v[74:77]
	ds_read_b128 v[232:235], v245 offset:17216
	s_waitcnt lgkmcnt(3)
	v_mfma_f32_16x16x32_bf16 v[74:77], v[236:239], v[106:109], v[74:77]
	ds_read_b128 v[236:239], v245 offset:17280
	s_waitcnt lgkmcnt(3)
	v_mfma_f32_16x16x32_bf16 v[74:77], v[240:243], v[110:113], v[74:77]
	ds_read_b128 v[240:243], v245 offset:17344
	s_waitcnt lgkmcnt(3)
	v_mfma_f32_16x16x32_bf16 v[74:77], v[228:231], v[114:117], v[74:77]
	ds_read_b128 v[228:231], v245 offset:25344
	s_waitcnt lgkmcnt(3)
	v_mfma_f32_16x16x32_bf16 v[74:77], v[232:235], v[118:121], v[74:77]
	ds_read_b128 v[232:235], v245 offset:25408
	s_waitcnt lgkmcnt(3)
	v_mfma_f32_16x16x32_bf16 v[74:77], v[236:239], v[122:125], v[74:77]
	ds_read_b128 v[236:239], v245 offset:25472
	s_waitcnt lgkmcnt(3)
	v_mfma_f32_16x16x32_bf16 v[74:77], v[240:243], v[224:227], v[74:77]
	ds_read_b128 v[240:243], v245 offset:25536
	s_waitcnt lgkmcnt(3)
	v_mfma_f32_16x16x32_bf16 v[78:81], v[228:231], v[98:101], 0
	ds_read_b128 v[228:231], v245 offset:25600
	s_waitcnt lgkmcnt(3)
	v_mfma_f32_16x16x32_bf16 v[78:81], v[232:235], v[102:105], v[78:81]
	ds_read_b128 v[232:235], v245 offset:25664
	s_waitcnt lgkmcnt(3)
	v_mfma_f32_16x16x32_bf16 v[78:81], v[236:239], v[106:109], v[78:81]
	ds_read_b128 v[236:239], v245 offset:25728
	s_waitcnt lgkmcnt(3)
	v_mfma_f32_16x16x32_bf16 v[78:81], v[240:243], v[110:113], v[78:81]
	ds_read_b128 v[240:243], v245 offset:25792
	s_waitcnt lgkmcnt(3)
	v_mfma_f32_16x16x32_bf16 v[78:81], v[228:231], v[114:117], v[78:81]
	ds_read_b128 v[228:231], v245 offset:33792
	s_waitcnt lgkmcnt(3)
	v_mfma_f32_16x16x32_bf16 v[78:81], v[232:235], v[118:121], v[78:81]
	ds_read_b128 v[232:235], v245 offset:33856
	s_waitcnt lgkmcnt(3)
	v_mfma_f32_16x16x32_bf16 v[78:81], v[236:239], v[122:125], v[78:81]
	ds_read_b128 v[236:239], v245 offset:33920
	s_waitcnt lgkmcnt(3)
	v_mfma_f32_16x16x32_bf16 v[78:81], v[240:243], v[224:227], v[78:81]
	ds_read_b128 v[240:243], v245 offset:33984
	s_waitcnt lgkmcnt(3)
	v_mfma_f32_16x16x32_bf16 v[82:85], v[228:231], v[98:101], 0
	ds_read_b128 v[228:231], v245 offset:34048
	s_waitcnt lgkmcnt(3)
	v_mfma_f32_16x16x32_bf16 v[82:85], v[232:235], v[102:105], v[82:85]
	ds_read_b128 v[232:235], v245 offset:34112
	s_waitcnt lgkmcnt(3)
	v_mfma_f32_16x16x32_bf16 v[82:85], v[236:239], v[106:109], v[82:85]
	ds_read_b128 v[236:239], v245 offset:34176
	s_waitcnt lgkmcnt(3)
	v_mfma_f32_16x16x32_bf16 v[82:85], v[240:243], v[110:113], v[82:85]
	ds_read_b128 v[240:243], v245 offset:34240
	s_waitcnt lgkmcnt(3)
	v_mfma_f32_16x16x32_bf16 v[82:85], v[228:231], v[114:117], v[82:85]
	ds_read_b128 v[228:231], v245 offset:42240
	s_waitcnt lgkmcnt(3)
	v_mfma_f32_16x16x32_bf16 v[82:85], v[232:235], v[118:121], v[82:85]
	ds_read_b128 v[232:235], v245 offset:42304
	s_waitcnt lgkmcnt(3)
	v_mfma_f32_16x16x32_bf16 v[82:85], v[236:239], v[122:125], v[82:85]
	ds_read_b128 v[236:239], v245 offset:42368
	s_waitcnt lgkmcnt(3)
	v_mfma_f32_16x16x32_bf16 v[82:85], v[240:243], v[224:227], v[82:85]
	ds_read_b128 v[240:243], v245 offset:42432
	s_waitcnt lgkmcnt(3)
	v_mfma_f32_16x16x32_bf16 v[86:89], v[228:231], v[98:101], 0
	ds_read_b128 v[228:231], v245 offset:42496
	s_waitcnt lgkmcnt(3)
	v_mfma_f32_16x16x32_bf16 v[86:89], v[232:235], v[102:105], v[86:89]
	ds_read_b128 v[232:235], v245 offset:42560
	s_waitcnt lgkmcnt(3)
	v_mfma_f32_16x16x32_bf16 v[86:89], v[236:239], v[106:109], v[86:89]
	ds_read_b128 v[236:239], v245 offset:42624
	s_waitcnt lgkmcnt(3)
	v_mfma_f32_16x16x32_bf16 v[86:89], v[240:243], v[110:113], v[86:89]
	ds_read_b128 v[240:243], v245 offset:42688
	s_waitcnt lgkmcnt(3)
	v_mfma_f32_16x16x32_bf16 v[86:89], v[228:231], v[114:117], v[86:89]
	ds_read_b128 v[228:231], v245 offset:50688
	s_waitcnt lgkmcnt(3)
	v_mfma_f32_16x16x32_bf16 v[86:89], v[232:235], v[118:121], v[86:89]
	ds_read_b128 v[232:235], v245 offset:50752
	s_waitcnt lgkmcnt(3)
	v_mfma_f32_16x16x32_bf16 v[86:89], v[236:239], v[122:125], v[86:89]
	ds_read_b128 v[236:239], v245 offset:50816
	s_waitcnt lgkmcnt(3)
	v_mfma_f32_16x16x32_bf16 v[86:89], v[240:243], v[224:227], v[86:89]
	ds_read_b128 v[240:243], v245 offset:50880
	s_waitcnt lgkmcnt(3)
	v_mfma_f32_16x16x32_bf16 v[90:93], v[228:231], v[98:101], 0
	ds_read_b128 v[228:231], v245 offset:50944
	s_waitcnt lgkmcnt(3)
	v_mfma_f32_16x16x32_bf16 v[90:93], v[232:235], v[102:105], v[90:93]
	ds_read_b128 v[232:235], v245 offset:51008
	s_waitcnt lgkmcnt(3)
	v_mfma_f32_16x16x32_bf16 v[90:93], v[236:239], v[106:109], v[90:93]
	ds_read_b128 v[236:239], v245 offset:51072
	s_waitcnt lgkmcnt(3)
	v_mfma_f32_16x16x32_bf16 v[90:93], v[240:243], v[110:113], v[90:93]
	ds_read_b128 v[240:243], v245 offset:51136
	s_waitcnt lgkmcnt(3)
	v_mfma_f32_16x16x32_bf16 v[90:93], v[228:231], v[114:117], v[90:93]
	ds_read_b128 v[228:231], v245 offset:59136
	s_waitcnt lgkmcnt(3)
	v_mfma_f32_16x16x32_bf16 v[90:93], v[232:235], v[118:121], v[90:93]
	ds_read_b128 v[232:235], v245 offset:59200
	s_waitcnt lgkmcnt(3)
	v_mfma_f32_16x16x32_bf16 v[90:93], v[236:239], v[122:125], v[90:93]
	ds_read_b128 v[236:239], v245 offset:59264
	s_waitcnt lgkmcnt(3)
	v_mfma_f32_16x16x32_bf16 v[90:93], v[240:243], v[224:227], v[90:93]
	ds_read_b128 v[240:243], v245 offset:59328
	s_waitcnt lgkmcnt(3)
	v_mfma_f32_16x16x32_bf16 v[94:97], v[228:231], v[98:101], 0
	ds_read_b128 v[228:231], v245 offset:59392
	s_waitcnt lgkmcnt(3)
	v_mfma_f32_16x16x32_bf16 v[94:97], v[232:235], v[102:105], v[94:97]
	ds_read_b128 v[232:235], v245 offset:59456
	s_waitcnt lgkmcnt(3)
	v_mfma_f32_16x16x32_bf16 v[94:97], v[236:239], v[106:109], v[94:97]
	ds_read_b128 v[236:239], v245 offset:59520
	s_waitcnt lgkmcnt(3)
	v_mfma_f32_16x16x32_bf16 v[94:97], v[240:243], v[110:113], v[94:97]
	ds_read_b128 v[240:243], v245 offset:59584
	s_waitcnt lgkmcnt(3)
	v_mfma_f32_16x16x32_bf16 v[94:97], v[228:231], v[114:117], v[94:97]
	s_waitcnt lgkmcnt(2)
	v_mfma_f32_16x16x32_bf16 v[94:97], v[232:235], v[118:121], v[94:97]
	s_waitcnt lgkmcnt(1)
	v_mfma_f32_16x16x32_bf16 v[94:97], v[236:239], v[122:125], v[94:97]
	s_waitcnt lgkmcnt(0)
	v_mfma_f32_16x16x32_bf16 v[94:97], v[240:243], v[224:227], v[94:97]
	v_max3_f32 v248, v34, v35, v205
	v_max3_f32 v248, v248, v36, v37
	v_max3_f32 v248, v248, v38, v39
	v_max3_f32 v248, v248, v40, v41
	v_max3_f32 v248, v248, v42, v43
	v_max3_f32 v248, v248, v44, v45
	v_max3_f32 v248, v248, v46, v47
	v_max3_f32 v248, v248, v48, v49
	v_max3_f32 v248, v248, v50, v51
	v_max3_f32 v248, v248, v52, v53
	v_max3_f32 v248, v248, v54, v55
	v_max3_f32 v248, v248, v56, v57
	v_max3_f32 v248, v248, v58, v59
	v_max3_f32 v248, v248, v60, v61
	v_max3_f32 v248, v248, v62, v63
	v_max3_f32 v248, v248, v64, v65
	v_max3_f32 v248, v248, v66, v67
	v_max3_f32 v248, v248, v68, v69
	v_max3_f32 v248, v248, v70, v71
	v_max3_f32 v248, v248, v72, v73
	v_max3_f32 v248, v248, v74, v75
	v_max3_f32 v248, v248, v76, v77
	v_max3_f32 v248, v248, v78, v79
	v_max3_f32 v248, v248, v80, v81
	v_max3_f32 v248, v248, v82, v83
	v_max3_f32 v248, v248, v84, v85
	v_max3_f32 v248, v248, v86, v87
	v_max3_f32 v248, v248, v88, v89
	v_max3_f32 v248, v248, v90, v91
	v_max3_f32 v248, v248, v92, v93
	v_max3_f32 v248, v248, v94, v95
	v_max3_f32 v248, v248, v96, v97
	v_xor_b32_e32 v131, 16, v195
	v_lshlrev_b32_e32 v131, 2, v131
	ds_bpermute_b32 v131, v131, v248
	s_waitcnt lgkmcnt(0)
	v_max_f32_e32 v248, v248, v131
	v_xor_b32_e32 v131, 32, v195
	v_lshlrev_b32_e32 v131, 2, v131
	ds_bpermute_b32 v131, v131, v248
	s_waitcnt lgkmcnt(0)
	v_max_f32_e32 v248, v248, v131
	v_mul_f32_e32 v248, 0xbdb8aa3b, v248
	v_fmamk_f32 v34, v34, 0x3db8aa3b, v248
	v_fmamk_f32 v35, v35, 0x3db8aa3b, v248
	v_fmamk_f32 v36, v36, 0x3db8aa3b, v248
	v_fmamk_f32 v37, v37, 0x3db8aa3b, v248
	v_exp_f32_e32 v34, v34
	v_exp_f32_e32 v35, v35
	v_exp_f32_e32 v36, v36
	v_exp_f32_e32 v37, v37
	v_fmamk_f32 v38, v38, 0x3db8aa3b, v248
	v_fmamk_f32 v39, v39, 0x3db8aa3b, v248
	v_fmamk_f32 v40, v40, 0x3db8aa3b, v248
	v_fmamk_f32 v41, v41, 0x3db8aa3b, v248
	v_exp_f32_e32 v38, v38
	v_exp_f32_e32 v39, v39
	v_exp_f32_e32 v40, v40
	v_exp_f32_e32 v41, v41
	v_add_f32_e32 v249, 0, v34
	v_add_f32_e32 v249, v249, v35
	v_add_f32_e32 v249, v249, v36
	v_add_f32_e32 v249, v249, v37
	v_fmamk_f32 v42, v42, 0x3db8aa3b, v248
	v_fmamk_f32 v43, v43, 0x3db8aa3b, v248
	v_fmamk_f32 v44, v44, 0x3db8aa3b, v248
	v_fmamk_f32 v45, v45, 0x3db8aa3b, v248
	v_exp_f32_e32 v42, v42
	v_exp_f32_e32 v43, v43
	v_exp_f32_e32 v44, v44
	v_exp_f32_e32 v45, v45
	v_add_f32_e32 v249, v249, v38
	v_add_f32_e32 v249, v249, v39
	v_add_f32_e32 v249, v249, v40
	v_add_f32_e32 v249, v249, v41
	v_fmamk_f32 v46, v46, 0x3db8aa3b, v248
	v_fmamk_f32 v47, v47, 0x3db8aa3b, v248
	v_fmamk_f32 v48, v48, 0x3db8aa3b, v248
	v_fmamk_f32 v49, v49, 0x3db8aa3b, v248
	v_exp_f32_e32 v46, v46
	v_exp_f32_e32 v47, v47
	v_exp_f32_e32 v48, v48
	v_exp_f32_e32 v49, v49
	v_add_f32_e32 v249, v249, v42
	v_add_f32_e32 v249, v249, v43
	v_add_f32_e32 v249, v249, v44
	v_add_f32_e32 v249, v249, v45
	v_fmamk_f32 v50, v50, 0x3db8aa3b, v248
	v_fmamk_f32 v51, v51, 0x3db8aa3b, v248
	v_fmamk_f32 v52, v52, 0x3db8aa3b, v248
	v_fmamk_f32 v53, v53, 0x3db8aa3b, v248
	v_exp_f32_e32 v50, v50
	v_exp_f32_e32 v51, v51
	v_exp_f32_e32 v52, v52
	v_exp_f32_e32 v53, v53
	v_add_f32_e32 v249, v249, v46
	v_add_f32_e32 v249, v249, v47
	v_add_f32_e32 v249, v249, v48
	v_add_f32_e32 v249, v249, v49
	v_fmamk_f32 v54, v54, 0x3db8aa3b, v248
	v_fmamk_f32 v55, v55, 0x3db8aa3b, v248
	v_fmamk_f32 v56, v56, 0x3db8aa3b, v248
	v_fmamk_f32 v57, v57, 0x3db8aa3b, v248
	v_exp_f32_e32 v54, v54
	v_exp_f32_e32 v55, v55
	v_exp_f32_e32 v56, v56
	v_exp_f32_e32 v57, v57
	v_add_f32_e32 v249, v249, v50
	v_add_f32_e32 v249, v249, v51
	v_add_f32_e32 v249, v249, v52
	v_add_f32_e32 v249, v249, v53
	v_fmamk_f32 v58, v58, 0x3db8aa3b, v248
	v_fmamk_f32 v59, v59, 0x3db8aa3b, v248
	v_fmamk_f32 v60, v60, 0x3db8aa3b, v248
	v_fmamk_f32 v61, v61, 0x3db8aa3b, v248
	v_exp_f32_e32 v58, v58
	v_exp_f32_e32 v59, v59
	v_exp_f32_e32 v60, v60
	v_exp_f32_e32 v61, v61
	v_add_f32_e32 v249, v249, v54
	v_add_f32_e32 v249, v249, v55
	v_add_f32_e32 v249, v249, v56
	v_add_f32_e32 v249, v249, v57
	v_fmamk_f32 v62, v62, 0x3db8aa3b, v248
	v_fmamk_f32 v63, v63, 0x3db8aa3b, v248
	v_fmamk_f32 v64, v64, 0x3db8aa3b, v248
	v_fmamk_f32 v65, v65, 0x3db8aa3b, v248
	v_exp_f32_e32 v62, v62
	v_exp_f32_e32 v63, v63
	v_exp_f32_e32 v64, v64
	v_exp_f32_e32 v65, v65
	v_add_f32_e32 v249, v249, v58
	v_add_f32_e32 v249, v249, v59
	v_add_f32_e32 v249, v249, v60
	v_add_f32_e32 v249, v249, v61
	v_fmamk_f32 v66, v66, 0x3db8aa3b, v248
	v_fmamk_f32 v67, v67, 0x3db8aa3b, v248
	v_fmamk_f32 v68, v68, 0x3db8aa3b, v248
	v_fmamk_f32 v69, v69, 0x3db8aa3b, v248
	v_exp_f32_e32 v66, v66
	v_exp_f32_e32 v67, v67
	v_exp_f32_e32 v68, v68
	v_exp_f32_e32 v69, v69
	v_add_f32_e32 v249, v249, v62
	v_add_f32_e32 v249, v249, v63
	v_add_f32_e32 v249, v249, v64
	v_add_f32_e32 v249, v249, v65
	v_fmamk_f32 v70, v70, 0x3db8aa3b, v248
	v_fmamk_f32 v71, v71, 0x3db8aa3b, v248
	v_fmamk_f32 v72, v72, 0x3db8aa3b, v248
	v_fmamk_f32 v73, v73, 0x3db8aa3b, v248
	v_exp_f32_e32 v70, v70
	v_exp_f32_e32 v71, v71
	v_exp_f32_e32 v72, v72
	v_exp_f32_e32 v73, v73
	v_add_f32_e32 v249, v249, v66
	v_add_f32_e32 v249, v249, v67
	v_add_f32_e32 v249, v249, v68
	v_add_f32_e32 v249, v249, v69
	v_fmamk_f32 v74, v74, 0x3db8aa3b, v248
	v_fmamk_f32 v75, v75, 0x3db8aa3b, v248
	v_fmamk_f32 v76, v76, 0x3db8aa3b, v248
	v_fmamk_f32 v77, v77, 0x3db8aa3b, v248
	v_exp_f32_e32 v74, v74
	v_exp_f32_e32 v75, v75
	v_exp_f32_e32 v76, v76
	v_exp_f32_e32 v77, v77
	v_add_f32_e32 v249, v249, v70
	v_add_f32_e32 v249, v249, v71
	v_add_f32_e32 v249, v249, v72
	v_add_f32_e32 v249, v249, v73
	v_fmamk_f32 v78, v78, 0x3db8aa3b, v248
	v_fmamk_f32 v79, v79, 0x3db8aa3b, v248
	v_fmamk_f32 v80, v80, 0x3db8aa3b, v248
	v_fmamk_f32 v81, v81, 0x3db8aa3b, v248
	v_exp_f32_e32 v78, v78
	v_exp_f32_e32 v79, v79
	v_exp_f32_e32 v80, v80
	v_exp_f32_e32 v81, v81
	v_add_f32_e32 v249, v249, v74
	v_add_f32_e32 v249, v249, v75
	v_add_f32_e32 v249, v249, v76
	v_add_f32_e32 v249, v249, v77
	v_fmamk_f32 v82, v82, 0x3db8aa3b, v248
	v_fmamk_f32 v83, v83, 0x3db8aa3b, v248
	v_fmamk_f32 v84, v84, 0x3db8aa3b, v248
	v_fmamk_f32 v85, v85, 0x3db8aa3b, v248
	v_exp_f32_e32 v82, v82
	v_exp_f32_e32 v83, v83
	v_exp_f32_e32 v84, v84
	v_exp_f32_e32 v85, v85
	v_add_f32_e32 v249, v249, v78
	v_add_f32_e32 v249, v249, v79
	v_add_f32_e32 v249, v249, v80
	v_add_f32_e32 v249, v249, v81
	v_fmamk_f32 v86, v86, 0x3db8aa3b, v248
	v_fmamk_f32 v87, v87, 0x3db8aa3b, v248
	v_fmamk_f32 v88, v88, 0x3db8aa3b, v248
	v_fmamk_f32 v89, v89, 0x3db8aa3b, v248
	v_exp_f32_e32 v86, v86
	v_exp_f32_e32 v87, v87
	v_exp_f32_e32 v88, v88
	v_exp_f32_e32 v89, v89
	v_add_f32_e32 v249, v249, v82
	v_add_f32_e32 v249, v249, v83
	v_add_f32_e32 v249, v249, v84
	v_add_f32_e32 v249, v249, v85
	v_fmamk_f32 v90, v90, 0x3db8aa3b, v248
	v_fmamk_f32 v91, v91, 0x3db8aa3b, v248
	v_fmamk_f32 v92, v92, 0x3db8aa3b, v248
	v_fmamk_f32 v93, v93, 0x3db8aa3b, v248
	v_exp_f32_e32 v90, v90
	v_exp_f32_e32 v91, v91
	v_exp_f32_e32 v92, v92
	v_exp_f32_e32 v93, v93
	v_add_f32_e32 v249, v249, v86
	v_add_f32_e32 v249, v249, v87
	v_add_f32_e32 v249, v249, v88
	v_add_f32_e32 v249, v249, v89
	v_fmamk_f32 v94, v94, 0x3db8aa3b, v248
	v_fmamk_f32 v95, v95, 0x3db8aa3b, v248
	v_fmamk_f32 v96, v96, 0x3db8aa3b, v248
	v_fmamk_f32 v97, v97, 0x3db8aa3b, v248
	v_exp_f32_e32 v94, v94
	v_exp_f32_e32 v95, v95
	v_exp_f32_e32 v96, v96
	v_exp_f32_e32 v97, v97
	v_add_f32_e32 v249, v249, v90
	v_add_f32_e32 v249, v249, v91
	v_add_f32_e32 v249, v249, v92
	v_add_f32_e32 v249, v249, v93
	s_nop 0
	v_add_f32_e32 v249, v249, v94
	v_add_f32_e32 v249, v249, v95
	v_add_f32_e32 v249, v249, v96
	v_add_f32_e32 v249, v249, v97
	v_xor_b32_e32 v131, 16, v195
	v_lshlrev_b32_e32 v131, 2, v131
	ds_bpermute_b32 v131, v131, v249
	s_waitcnt lgkmcnt(0)
	v_add_f32_e32 v249, v249, v131
	v_xor_b32_e32 v131, 32, v195
	v_lshlrev_b32_e32 v131, 2, v131
	ds_bpermute_b32 v131, v131, v249
	s_waitcnt lgkmcnt(0)
	v_add_f32_e32 v249, v249, v131
	v_rcp_f32_e32 v135, v249
	v_cvt_pk_bf16_f32 v34, v34, v35
	v_cvt_pk_bf16_f32 v35, v36, v37
	v_cvt_pk_bf16_f32 v36, v38, v39
	v_cvt_pk_bf16_f32 v37, v40, v41
	v_cvt_pk_bf16_f32 v38, v42, v43
	v_cvt_pk_bf16_f32 v39, v44, v45
	v_cvt_pk_bf16_f32 v40, v46, v47
	v_cvt_pk_bf16_f32 v41, v48, v49
	v_cvt_pk_bf16_f32 v42, v50, v51
	v_cvt_pk_bf16_f32 v43, v52, v53
	v_cvt_pk_bf16_f32 v44, v54, v55
	v_cvt_pk_bf16_f32 v45, v56, v57
	v_cvt_pk_bf16_f32 v46, v58, v59
	v_cvt_pk_bf16_f32 v47, v60, v61
	v_cvt_pk_bf16_f32 v48, v62, v63
	v_cvt_pk_bf16_f32 v49, v64, v65
	v_cvt_pk_bf16_f32 v50, v66, v67
	v_cvt_pk_bf16_f32 v51, v68, v69
	v_cvt_pk_bf16_f32 v52, v70, v71
	v_cvt_pk_bf16_f32 v53, v72, v73
	v_cvt_pk_bf16_f32 v54, v74, v75
	v_cvt_pk_bf16_f32 v55, v76, v77
	v_cvt_pk_bf16_f32 v56, v78, v79
	v_cvt_pk_bf16_f32 v57, v80, v81
	v_cvt_pk_bf16_f32 v58, v82, v83
	v_cvt_pk_bf16_f32 v59, v84, v85
	v_cvt_pk_bf16_f32 v60, v86, v87
	v_cvt_pk_bf16_f32 v61, v88, v89
	v_cvt_pk_bf16_f32 v62, v90, v91
	v_cvt_pk_bf16_f32 v63, v92, v93
	v_cvt_pk_bf16_f32 v64, v94, v95
	v_cvt_pk_bf16_f32 v65, v96, v97
	v_mov_b32_e32 v131, v1
	s_mov_b32 s5, 0
	v_lshl_add_u64 v[86:87], s[0:1], 0, v[130:131]
	s_mov_b64 s[0:1], -1
	s_waitcnt lgkmcnt(0)
	s_barrier
